# phase F epilogue stores: write-through only on the last tile of each block, plain write-back stores on earlier tiles
# baseline (speedup 1.0000x reference)
; __device__ __forceinline__ u32x2 pack4(f32x4 v) { u32x2 r; r.x = cvt_pk(v[0], v[1]); r.y = cvt_pk(v[2], v[3]); return r; }
; __device__ __forceinline__ void store_pair16(u16* rowp32, u32x2 a, u32x2 b, int fq) {
;   auto rx = __builtin_amdgcn_permlane16_swap(a.x, b.x, false, false);
;   auto ry = __builtin_amdgcn_permlane16_swap(a.y, b.y, false, false);
;   u32x4 w = {rx[0], ry[0], rx[1], ry[1]};
;   *(u32x4*)(rowp32 + ((fq & 1) * 16 + (fq >> 1) * 8)) = w;
; }
; __device__ __forceinline__ void phaseF(const Params& p, const int wv, const int rep) {
;     ...
;       const float* rs_c = rs_l + (it & 1) * 256;
;       ACC_FOREACH_PAIR({
;         const float rstd = rs_c[rrow];
;         f32x4 o0 = v0 * rstd, o1 = v1 * rstd;
;         o0[0] = fmaxf(o0[0], 0.f); o0[1] = fmaxf(o0[1], 0.f); o0[2] = fmaxf(o0[2], 0.f); o0[3] = fmaxf(o0[3], 0.f);
;         o1[0] = fmaxf(o1[0], 0.f); o1[1] = fmaxf(o1[1], 0.f); o1[2] = fmaxf(o1[2], 0.f); o1[3] = fmaxf(o1[3], 0.f);
;         o0 = o0 * o0; o1 = o1 * o1;
;         store_pair16(ACT + (size_t)(brow + rrow) * 4096 + bcol + cb32, pack4(o0), pack4(o1), fq);
;       });
.LBB0_1065:
	s_lshl_b32 s38, s76, 10
	s_and_b32 s38, s38, 0x400
	s_add_i32 s38, s38, 16
	v_mbcnt_lo_u32_b32 v128, -1, 0
	v_mbcnt_hi_u32_b32 v128, -1, v128
	s_nop 0
	v_and_or_b32 v135, v128, 15, s66
	v_lshl_add_u32 v134, v135, 2, s38
	v_add_u32_e32 v134, 0x20000, v134
	s_waitcnt vmcnt(0)
	ds_read2_b32 v[136:137], v134 offset1:16
	v_and_b32_e32 v130, 16, v128
	v_ashrrev_i32_e32 v128, 2, v128
	s_lshl_b32 s38, s78, 1
	v_and_b32_e32 v128, -8, v128
	s_add_u32 s38, s2, s38
	v_add_u32_e32 v130, v128, v130
	s_waitcnt lgkmcnt(0)
	v_pk_mul_f32 v[126:127], v[126:127], v[136:137] op_sel_hi:[1,0]
	v_pk_mul_f32 v[124:125], v[124:125], v[136:137] op_sel_hi:[1,0]
	v_pk_mul_f32 v[122:123], v[122:123], v[136:137] op_sel_hi:[1,0]
	v_pk_mul_f32 v[120:121], v[120:121], v[136:137] op_sel_hi:[1,0]
	s_addc_u32 s39, s3, 0
	v_ashrrev_i32_e32 v131, 31, v130
	v_add_u32_e32 v128, s77, v135
	v_max_f32_e32 v124, 0, v124
	v_max_f32_e32 v125, 0, v125
	v_max_f32_e32 v126, 0, v126
	v_max_f32_e32 v127, 0, v127
	v_max_f32_e32 v120, 0, v120
	v_max_f32_e32 v121, 0, v121
	v_max_f32_e32 v122, 0, v122
	v_max_f32_e32 v123, 0, v123
	v_lshl_add_u64 v[130:131], v[130:131], 1, s[38:39]
	v_lshlrev_b64 v[138:139], 13, v[128:129]
	v_pk_mul_f32 v[126:127], v[126:127], v[126:127]
	v_pk_mul_f32 v[124:125], v[124:125], v[124:125]
	v_pk_mul_f32 v[140:141], v[122:123], v[122:123]
	v_pk_mul_f32 v[122:123], v[120:121], v[120:121]
	v_lshl_add_u64 v[138:139], v[130:131], 0, v[138:139]
	v_cvt_pk_bf16_f32 v120, v124, v125
	v_cvt_pk_bf16_f32 v121, v126, v127
	v_cvt_pk_bf16_f32 v122, v122, v123
	v_cvt_pk_bf16_f32 v123, v140, v141
	v_pk_mul_f32 v[118:119], v[118:119], v[136:137] op_sel_hi:[1,0]
	v_pk_mul_f32 v[116:117], v[116:117], v[136:137] op_sel_hi:[1,0]
	v_pk_mul_f32 v[114:115], v[114:115], v[136:137] op_sel_hi:[1,0]
	v_pk_mul_f32 v[112:113], v[112:113], v[136:137] op_sel_hi:[1,0]
	v_permlane16_swap_b32_e32 v120, v122
	v_permlane16_swap_b32_e32 v121, v123
	v_lshl_add_u64 v[124:125], v[138:139], 0, s[12:13]
	v_max_f32_e32 v116, 0, v116
	v_max_f32_e32 v117, 0, v117
	v_max_f32_e32 v118, 0, v118
	v_max_f32_e32 v119, 0, v119
	v_max_f32_e32 v112, 0, v112
	v_max_f32_e32 v113, 0, v113
	v_max_f32_e32 v114, 0, v114
	v_max_f32_e32 v115, 0, v115
	s_andn2_b64 exec, exec, s[36:37]
	global_store_dwordx4 v[124:125], v[120:123], off
	s_mov_b64 exec, s[36:37]
	global_store_dwordx4 v[124:125], v[120:123], off sc1
	s_mov_b64 exec, -1
	v_pk_mul_f32 v[118:119], v[118:119], v[118:119]
	v_pk_mul_f32 v[116:117], v[116:117], v[116:117]
	v_pk_mul_f32 v[120:121], v[114:115], v[114:115]
	v_pk_mul_f32 v[114:115], v[112:113], v[112:113]
	v_cvt_pk_bf16_f32 v112, v116, v117
	v_cvt_pk_bf16_f32 v113, v118, v119
	v_cvt_pk_bf16_f32 v114, v114, v115
	v_cvt_pk_bf16_f32 v115, v120, v121
	s_nop 0
	v_permlane16_swap_b32_e32 v112, v114
	v_permlane16_swap_b32_e32 v113, v115
	s_andn2_b64 exec, exec, s[36:37]
	global_store_dwordx4 v[124:125], v[112:115], off offset:256
	s_mov_b64 exec, s[36:37]
	global_store_dwordx4 v[124:125], v[112:115], off offset:256 sc1
	s_mov_b64 exec, -1
	s_add_i32 s76, s76, 1
	s_add_i32 s67, s67, s68
	v_mov_b32_e32 v114, v137
	v_pk_mul_f32 v[110:111], v[110:111], v[114:115] op_sel_hi:[1,0]
	v_pk_mul_f32 v[108:109], v[108:109], v[114:115] op_sel_hi:[1,0]
	v_pk_mul_f32 v[106:107], v[106:107], v[114:115] op_sel_hi:[1,0]
	v_pk_mul_f32 v[104:105], v[104:105], v[114:115] op_sel_hi:[1,0]
	v_add_u32_e32 v112, 16, v128
	v_mov_b32_e32 v113, v129
	v_max_f32_e32 v108, 0, v108
	v_max_f32_e32 v109, 0, v109
	v_max_f32_e32 v110, 0, v110
	v_max_f32_e32 v111, 0, v111
	v_max_f32_e32 v104, 0, v104
	v_max_f32_e32 v105, 0, v105
	v_max_f32_e32 v106, 0, v106
	v_max_f32_e32 v107, 0, v107
	v_lshlrev_b64 v[112:113], 13, v[112:113]
	v_pk_mul_f32 v[110:111], v[110:111], v[110:111]
	v_pk_mul_f32 v[108:109], v[108:109], v[108:109]
	v_pk_mul_f32 v[116:117], v[106:107], v[106:107]
	v_pk_mul_f32 v[106:107], v[104:105], v[104:105]
	v_lshl_add_u64 v[112:113], v[130:131], 0, v[112:113]
	v_cvt_pk_bf16_f32 v104, v108, v109
	v_cvt_pk_bf16_f32 v105, v110, v111
	v_cvt_pk_bf16_f32 v106, v106, v107
	v_cvt_pk_bf16_f32 v107, v116, v117
	v_pk_mul_f32 v[102:103], v[102:103], v[114:115] op_sel_hi:[1,0]
	v_pk_mul_f32 v[100:101], v[100:101], v[114:115] op_sel_hi:[1,0]
	v_pk_mul_f32 v[98:99], v[98:99], v[114:115] op_sel_hi:[1,0]
	v_pk_mul_f32 v[96:97], v[96:97], v[114:115] op_sel_hi:[1,0]
	v_permlane16_swap_b32_e32 v104, v106
	v_permlane16_swap_b32_e32 v105, v107
	v_lshl_add_u64 v[108:109], v[112:113], 0, s[12:13]
	v_max_f32_e32 v100, 0, v100
	v_max_f32_e32 v101, 0, v101
	v_max_f32_e32 v102, 0, v102
	v_max_f32_e32 v103, 0, v103
	v_max_f32_e32 v96, 0, v96
	v_max_f32_e32 v97, 0, v97
	v_max_f32_e32 v98, 0, v98
	v_max_f32_e32 v99, 0, v99
	s_andn2_b64 exec, exec, s[36:37]
	global_store_dwordx4 v[108:109], v[104:107], off
	s_mov_b64 exec, s[36:37]
	global_store_dwordx4 v[108:109], v[104:107], off sc1
	s_mov_b64 exec, -1
	v_pk_mul_f32 v[102:103], v[102:103], v[102:103]
	v_pk_mul_f32 v[100:101], v[100:101], v[100:101]
	v_pk_mul_f32 v[104:105], v[98:99], v[98:99]
	v_pk_mul_f32 v[98:99], v[96:97], v[96:97]
	v_cvt_pk_bf16_f32 v96, v100, v101
	v_cvt_pk_bf16_f32 v97, v102, v103
	v_cvt_pk_bf16_f32 v98, v98, v99
	v_cvt_pk_bf16_f32 v99, v104, v105
	s_nop 0
	v_permlane16_swap_b32_e32 v96, v98
	v_permlane16_swap_b32_e32 v97, v99
	s_andn2_b64 exec, exec, s[36:37]
	global_store_dwordx4 v[108:109], v[96:99], off offset:256
	s_mov_b64 exec, s[36:37]
	global_store_dwordx4 v[108:109], v[96:99], off offset:256 sc1
	s_mov_b64 exec, -1
	ds_read2_b32 v[96:97], v134 offset0:32 offset1:48
	s_andn2_b64 vcc, exec, s[36:37]
	v_add_u32_e32 v98, 32, v128
	v_mov_b32_e32 v99, v129
	v_lshlrev_b64 v[98:99], 13, v[98:99]
	s_waitcnt lgkmcnt(0)
; __device__ __forceinline__ u32x2 pack4(f32x4 v) { u32x2 r; r.x = cvt_pk(v[0], v[1]); r.y = cvt_pk(v[2], v[3]); return r; }
; __device__ __forceinline__ void store_pair16(u16* rowp32, u32x2 a, u32x2 b, int fq) {
;   auto rx = __builtin_amdgcn_permlane16_swap(a.x, b.x, false, false);
;   auto ry = __builtin_amdgcn_permlane16_swap(a.y, b.y, false, false);
;   u32x4 w = {rx[0], ry[0], rx[1], ry[1]};
;   *(u32x4*)(rowp32 + ((fq & 1) * 16 + (fq >> 1) * 8)) = w;
; }
; __device__ __forceinline__ void phaseF(const Params& p, const int wv, const int rep) {
;     ...
;       const float* rs_c = rs_l + (it & 1) * 256;
;       ACC_FOREACH_PAIR({
;         const float rstd = rs_c[rrow];
;         f32x4 o0 = v0 * rstd, o1 = v1 * rstd;
;         o0[0] = fmaxf(o0[0], 0.f); o0[1] = fmaxf(o0[1], 0.f); o0[2] = fmaxf(o0[2], 0.f); o0[3] = fmaxf(o0[3], 0.f);
;         o1[0] = fmaxf(o1[0], 0.f); o1[1] = fmaxf(o1[1], 0.f); o1[2] = fmaxf(o1[2], 0.f); o1[3] = fmaxf(o1[3], 0.f);
;         o0 = o0 * o0; o1 = o1 * o1;
;         store_pair16(ACT + (size_t)(brow + rrow) * 4096 + bcol + cb32, pack4(o0), pack4(o1), fq);
;       });
	v_pk_mul_f32 v[94:95], v[94:95], v[96:97] op_sel_hi:[1,0]
	v_pk_mul_f32 v[92:93], v[92:93], v[96:97] op_sel_hi:[1,0]
	v_pk_mul_f32 v[90:91], v[90:91], v[96:97] op_sel_hi:[1,0]
	v_pk_mul_f32 v[88:89], v[88:89], v[96:97] op_sel_hi:[1,0]
	v_max_f32_e32 v92, 0, v92
	v_max_f32_e32 v93, 0, v93
	v_max_f32_e32 v94, 0, v94
	v_max_f32_e32 v95, 0, v95
	v_max_f32_e32 v88, 0, v88
	v_max_f32_e32 v89, 0, v89
	v_max_f32_e32 v90, 0, v90
	v_max_f32_e32 v91, 0, v91
	v_pk_mul_f32 v[94:95], v[94:95], v[94:95]
	v_pk_mul_f32 v[92:93], v[92:93], v[92:93]
	v_pk_mul_f32 v[100:101], v[90:91], v[90:91]
	v_pk_mul_f32 v[90:91], v[88:89], v[88:89]
	v_lshl_add_u64 v[98:99], v[130:131], 0, v[98:99]
	v_cvt_pk_bf16_f32 v88, v92, v93
	v_cvt_pk_bf16_f32 v89, v94, v95
	v_cvt_pk_bf16_f32 v90, v90, v91
	v_cvt_pk_bf16_f32 v91, v100, v101
	v_pk_mul_f32 v[86:87], v[86:87], v[96:97] op_sel_hi:[1,0]
	v_pk_mul_f32 v[84:85], v[84:85], v[96:97] op_sel_hi:[1,0]
	v_pk_mul_f32 v[82:83], v[82:83], v[96:97] op_sel_hi:[1,0]
	v_pk_mul_f32 v[80:81], v[80:81], v[96:97] op_sel_hi:[1,0]
	v_permlane16_swap_b32_e32 v88, v90
	v_permlane16_swap_b32_e32 v89, v91
	v_lshl_add_u64 v[92:93], v[98:99], 0, s[12:13]
	v_max_f32_e32 v84, 0, v84
	v_max_f32_e32 v85, 0, v85
	v_max_f32_e32 v86, 0, v86
	v_max_f32_e32 v87, 0, v87
	v_max_f32_e32 v80, 0, v80
	v_max_f32_e32 v81, 0, v81
	v_max_f32_e32 v82, 0, v82
	v_max_f32_e32 v83, 0, v83
	s_andn2_b64 exec, exec, s[36:37]
	global_store_dwordx4 v[92:93], v[88:91], off
	s_mov_b64 exec, s[36:37]
	global_store_dwordx4 v[92:93], v[88:91], off sc1
	s_mov_b64 exec, -1
	v_pk_mul_f32 v[86:87], v[86:87], v[86:87]
	v_pk_mul_f32 v[84:85], v[84:85], v[84:85]
	v_pk_mul_f32 v[88:89], v[82:83], v[82:83]
	v_pk_mul_f32 v[82:83], v[80:81], v[80:81]
	v_cvt_pk_bf16_f32 v80, v84, v85
	v_cvt_pk_bf16_f32 v81, v86, v87
	v_cvt_pk_bf16_f32 v82, v82, v83
	v_cvt_pk_bf16_f32 v83, v88, v89
	s_nop 0
	v_permlane16_swap_b32_e32 v80, v82
	v_permlane16_swap_b32_e32 v81, v83
	s_andn2_b64 exec, exec, s[36:37]
	global_store_dwordx4 v[92:93], v[80:83], off offset:256
	s_mov_b64 exec, s[36:37]
	global_store_dwordx4 v[92:93], v[80:83], off offset:256 sc1
	s_mov_b64 exec, -1
	s_add_i32 s69, s69, s70
	s_nop 0
	v_mov_b32_e32 v82, v97
	v_pk_mul_f32 v[78:79], v[78:79], v[82:83] op_sel_hi:[1,0]
	v_pk_mul_f32 v[76:77], v[76:77], v[82:83] op_sel_hi:[1,0]
	v_pk_mul_f32 v[74:75], v[74:75], v[82:83] op_sel_hi:[1,0]
	v_pk_mul_f32 v[72:73], v[72:73], v[82:83] op_sel_hi:[1,0]
	v_add_u32_e32 v80, 48, v128
	v_mov_b32_e32 v81, v129
	v_max_f32_e32 v76, 0, v76
	v_max_f32_e32 v77, 0, v77
	v_max_f32_e32 v78, 0, v78
	v_max_f32_e32 v79, 0, v79
	v_max_f32_e32 v72, 0, v72
	v_max_f32_e32 v73, 0, v73
	v_max_f32_e32 v74, 0, v74
	v_max_f32_e32 v75, 0, v75
	v_lshlrev_b64 v[80:81], 13, v[80:81]
	v_pk_mul_f32 v[78:79], v[78:79], v[78:79]
	v_pk_mul_f32 v[76:77], v[76:77], v[76:77]
	v_pk_mul_f32 v[84:85], v[74:75], v[74:75]
	v_pk_mul_f32 v[74:75], v[72:73], v[72:73]
	v_lshl_add_u64 v[80:81], v[130:131], 0, v[80:81]
	v_cvt_pk_bf16_f32 v72, v76, v77
	v_cvt_pk_bf16_f32 v73, v78, v79
	v_cvt_pk_bf16_f32 v74, v74, v75
	v_cvt_pk_bf16_f32 v75, v84, v85
	v_pk_mul_f32 v[70:71], v[70:71], v[82:83] op_sel_hi:[1,0]
	v_pk_mul_f32 v[68:69], v[68:69], v[82:83] op_sel_hi:[1,0]
	v_pk_mul_f32 v[66:67], v[66:67], v[82:83] op_sel_hi:[1,0]
	v_pk_mul_f32 v[64:65], v[64:65], v[82:83] op_sel_hi:[1,0]
	v_permlane16_swap_b32_e32 v72, v74
	v_permlane16_swap_b32_e32 v73, v75
	v_lshl_add_u64 v[76:77], v[80:81], 0, s[12:13]
	v_max_f32_e32 v68, 0, v68
	v_max_f32_e32 v69, 0, v69
	v_max_f32_e32 v70, 0, v70
	v_max_f32_e32 v71, 0, v71
	v_max_f32_e32 v64, 0, v64
	v_max_f32_e32 v65, 0, v65
	v_max_f32_e32 v66, 0, v66
	v_max_f32_e32 v67, 0, v67
	s_andn2_b64 exec, exec, s[36:37]
	global_store_dwordx4 v[76:77], v[72:75], off
	s_mov_b64 exec, s[36:37]
	global_store_dwordx4 v[76:77], v[72:75], off sc1
	s_mov_b64 exec, -1
	v_pk_mul_f32 v[70:71], v[70:71], v[70:71]
	v_pk_mul_f32 v[68:69], v[68:69], v[68:69]
	v_pk_mul_f32 v[72:73], v[66:67], v[66:67]
	v_pk_mul_f32 v[66:67], v[64:65], v[64:65]
	v_cvt_pk_bf16_f32 v64, v68, v69
	v_cvt_pk_bf16_f32 v65, v70, v71
	v_cvt_pk_bf16_f32 v66, v66, v67
	v_cvt_pk_bf16_f32 v67, v72, v73
	s_nop 0
	v_permlane16_swap_b32_e32 v64, v66
	v_permlane16_swap_b32_e32 v65, v67
	s_andn2_b64 exec, exec, s[36:37]
	global_store_dwordx4 v[76:77], v[64:67], off offset:256
	s_mov_b64 exec, s[36:37]
	global_store_dwordx4 v[76:77], v[64:67], off offset:256 sc1
	s_mov_b64 exec, -1
	ds_read2_b32 v[64:65], v134 offset0:128 offset1:144
	s_waitcnt lgkmcnt(0)
; __device__ __forceinline__ u32x2 pack4(f32x4 v) { u32x2 r; r.x = cvt_pk(v[0], v[1]); r.y = cvt_pk(v[2], v[3]); return r; }
; __device__ __forceinline__ void store_pair16(u16* rowp32, u32x2 a, u32x2 b, int fq) {
;   auto rx = __builtin_amdgcn_permlane16_swap(a.x, b.x, false, false);
;   auto ry = __builtin_amdgcn_permlane16_swap(a.y, b.y, false, false);
;   u32x4 w = {rx[0], ry[0], rx[1], ry[1]};
;   *(u32x4*)(rowp32 + ((fq & 1) * 16 + (fq >> 1) * 8)) = w;
; }
; __device__ __forceinline__ void phaseF(const Params& p, const int wv, const int rep) {
;     ...
;       const float* rs_c = rs_l + (it & 1) * 256;
;       ACC_FOREACH_PAIR({
;         const float rstd = rs_c[rrow];
;         f32x4 o0 = v0 * rstd, o1 = v1 * rstd;
;         o0[0] = fmaxf(o0[0], 0.f); o0[1] = fmaxf(o0[1], 0.f); o0[2] = fmaxf(o0[2], 0.f); o0[3] = fmaxf(o0[3], 0.f);
;         o1[0] = fmaxf(o1[0], 0.f); o1[1] = fmaxf(o1[1], 0.f); o1[2] = fmaxf(o1[2], 0.f); o1[3] = fmaxf(o1[3], 0.f);
;         o0 = o0 * o0; o1 = o1 * o1;
;         store_pair16(ACT + (size_t)(brow + rrow) * 4096 + bcol + cb32, pack4(o0), pack4(o1), fq);
;       });
	v_pk_mul_f32 v[62:63], v[62:63], v[64:65] op_sel_hi:[1,0]
	v_pk_mul_f32 v[60:61], v[60:61], v[64:65] op_sel_hi:[1,0]
	v_pk_mul_f32 v[58:59], v[58:59], v[64:65] op_sel_hi:[1,0]
	v_pk_mul_f32 v[56:57], v[56:57], v[64:65] op_sel_hi:[1,0]
	v_add_u32_e32 v66, 0x80, v128
	v_mov_b32_e32 v67, v129
	v_max_f32_e32 v60, 0, v60
	v_max_f32_e32 v61, 0, v61
	v_max_f32_e32 v62, 0, v62
	v_max_f32_e32 v63, 0, v63
	v_max_f32_e32 v56, 0, v56
	v_max_f32_e32 v57, 0, v57
	v_max_f32_e32 v58, 0, v58
	v_max_f32_e32 v59, 0, v59
	v_lshlrev_b64 v[66:67], 13, v[66:67]
	v_pk_mul_f32 v[62:63], v[62:63], v[62:63]
	v_pk_mul_f32 v[60:61], v[60:61], v[60:61]
	v_pk_mul_f32 v[68:69], v[58:59], v[58:59]
	v_pk_mul_f32 v[58:59], v[56:57], v[56:57]
	v_lshl_add_u64 v[66:67], v[130:131], 0, v[66:67]
	v_cvt_pk_bf16_f32 v56, v60, v61
	v_cvt_pk_bf16_f32 v57, v62, v63
	v_cvt_pk_bf16_f32 v58, v58, v59
	v_cvt_pk_bf16_f32 v59, v68, v69
	v_pk_mul_f32 v[54:55], v[54:55], v[64:65] op_sel_hi:[1,0]
	v_pk_mul_f32 v[52:53], v[52:53], v[64:65] op_sel_hi:[1,0]
	v_pk_mul_f32 v[50:51], v[50:51], v[64:65] op_sel_hi:[1,0]
	v_pk_mul_f32 v[48:49], v[48:49], v[64:65] op_sel_hi:[1,0]
	v_permlane16_swap_b32_e32 v56, v58
	v_permlane16_swap_b32_e32 v57, v59
	v_lshl_add_u64 v[60:61], v[66:67], 0, s[12:13]
	v_max_f32_e32 v52, 0, v52
	v_max_f32_e32 v53, 0, v53
	v_max_f32_e32 v54, 0, v54
	v_max_f32_e32 v55, 0, v55
	v_max_f32_e32 v48, 0, v48
	v_max_f32_e32 v49, 0, v49
	v_max_f32_e32 v50, 0, v50
	v_max_f32_e32 v51, 0, v51
	s_andn2_b64 exec, exec, s[36:37]
	global_store_dwordx4 v[60:61], v[56:59], off
	s_mov_b64 exec, s[36:37]
	global_store_dwordx4 v[60:61], v[56:59], off sc1
	s_mov_b64 exec, -1
	v_pk_mul_f32 v[54:55], v[54:55], v[54:55]
	v_pk_mul_f32 v[52:53], v[52:53], v[52:53]
	v_pk_mul_f32 v[56:57], v[50:51], v[50:51]
	v_pk_mul_f32 v[50:51], v[48:49], v[48:49]
	v_cvt_pk_bf16_f32 v48, v52, v53
	v_cvt_pk_bf16_f32 v49, v54, v55
	v_cvt_pk_bf16_f32 v50, v50, v51
	v_cvt_pk_bf16_f32 v51, v56, v57
	s_nop 0
	v_permlane16_swap_b32_e32 v48, v50
	v_permlane16_swap_b32_e32 v49, v51
	s_andn2_b64 exec, exec, s[36:37]
	global_store_dwordx4 v[60:61], v[48:51], off offset:256
	s_mov_b64 exec, s[36:37]
	global_store_dwordx4 v[60:61], v[48:51], off offset:256 sc1
	s_mov_b64 exec, -1
	s_nop 1
	v_mov_b32_e32 v50, v65
	v_pk_mul_f32 v[46:47], v[46:47], v[50:51] op_sel_hi:[1,0]
	v_pk_mul_f32 v[44:45], v[44:45], v[50:51] op_sel_hi:[1,0]
	v_pk_mul_f32 v[42:43], v[42:43], v[50:51] op_sel_hi:[1,0]
	v_pk_mul_f32 v[40:41], v[40:41], v[50:51] op_sel_hi:[1,0]
	v_add_u32_e32 v48, 0x90, v128
	v_mov_b32_e32 v49, v129
	v_max_f32_e32 v44, 0, v44
	v_max_f32_e32 v45, 0, v45
	v_max_f32_e32 v46, 0, v46
	v_max_f32_e32 v47, 0, v47
	v_max_f32_e32 v40, 0, v40
	v_max_f32_e32 v41, 0, v41
	v_max_f32_e32 v42, 0, v42
	v_max_f32_e32 v43, 0, v43
	v_lshlrev_b64 v[48:49], 13, v[48:49]
	v_pk_mul_f32 v[46:47], v[46:47], v[46:47]
	v_pk_mul_f32 v[44:45], v[44:45], v[44:45]
	v_pk_mul_f32 v[52:53], v[42:43], v[42:43]
	v_pk_mul_f32 v[42:43], v[40:41], v[40:41]
	v_lshl_add_u64 v[48:49], v[130:131], 0, v[48:49]
	v_cvt_pk_bf16_f32 v40, v44, v45
	v_cvt_pk_bf16_f32 v41, v46, v47
	v_cvt_pk_bf16_f32 v42, v42, v43
	v_cvt_pk_bf16_f32 v43, v52, v53
	v_pk_mul_f32 v[38:39], v[38:39], v[50:51] op_sel_hi:[1,0]
	v_pk_mul_f32 v[36:37], v[36:37], v[50:51] op_sel_hi:[1,0]
	v_pk_mul_f32 v[34:35], v[34:35], v[50:51] op_sel_hi:[1,0]
	v_pk_mul_f32 v[32:33], v[32:33], v[50:51] op_sel_hi:[1,0]
	v_permlane16_swap_b32_e32 v40, v42
	v_permlane16_swap_b32_e32 v41, v43
	v_lshl_add_u64 v[44:45], v[48:49], 0, s[12:13]
	v_max_f32_e32 v36, 0, v36
	v_max_f32_e32 v37, 0, v37
	v_max_f32_e32 v38, 0, v38
	v_max_f32_e32 v39, 0, v39
	v_max_f32_e32 v32, 0, v32
	v_max_f32_e32 v33, 0, v33
	v_max_f32_e32 v34, 0, v34
	v_max_f32_e32 v35, 0, v35
	s_andn2_b64 exec, exec, s[36:37]
	global_store_dwordx4 v[44:45], v[40:43], off
	s_mov_b64 exec, s[36:37]
	global_store_dwordx4 v[44:45], v[40:43], off sc1
	s_mov_b64 exec, -1
	v_pk_mul_f32 v[38:39], v[38:39], v[38:39]
	v_pk_mul_f32 v[36:37], v[36:37], v[36:37]
	v_pk_mul_f32 v[40:41], v[34:35], v[34:35]
	v_pk_mul_f32 v[34:35], v[32:33], v[32:33]
	v_cvt_pk_bf16_f32 v32, v36, v37
	v_cvt_pk_bf16_f32 v33, v38, v39
	v_cvt_pk_bf16_f32 v34, v34, v35
	v_cvt_pk_bf16_f32 v35, v40, v41
	s_nop 0
	v_permlane16_swap_b32_e32 v32, v34
	v_permlane16_swap_b32_e32 v33, v35
	s_andn2_b64 exec, exec, s[36:37]
	global_store_dwordx4 v[44:45], v[32:35], off offset:256
	s_mov_b64 exec, s[36:37]
	global_store_dwordx4 v[44:45], v[32:35], off offset:256 sc1
	s_mov_b64 exec, -1
	ds_read2_b32 v[32:33], v134 offset0:160 offset1:176
	s_waitcnt lgkmcnt(0)
; __device__ __forceinline__ u32x2 pack4(f32x4 v) { u32x2 r; r.x = cvt_pk(v[0], v[1]); r.y = cvt_pk(v[2], v[3]); return r; }
; __device__ __forceinline__ void store_pair16(u16* rowp32, u32x2 a, u32x2 b, int fq) {
;   auto rx = __builtin_amdgcn_permlane16_swap(a.x, b.x, false, false);
;   auto ry = __builtin_amdgcn_permlane16_swap(a.y, b.y, false, false);
;   u32x4 w = {rx[0], ry[0], rx[1], ry[1]};
;   *(u32x4*)(rowp32 + ((fq & 1) * 16 + (fq >> 1) * 8)) = w;
; }
; __device__ __forceinline__ void phaseF(const Params& p, const int wv, const int rep) {
;     ...
;       const float* rs_c = rs_l + (it & 1) * 256;
;       ACC_FOREACH_PAIR({
;         const float rstd = rs_c[rrow];
;         f32x4 o0 = v0 * rstd, o1 = v1 * rstd;
;         o0[0] = fmaxf(o0[0], 0.f); o0[1] = fmaxf(o0[1], 0.f); o0[2] = fmaxf(o0[2], 0.f); o0[3] = fmaxf(o0[3], 0.f);
;         o1[0] = fmaxf(o1[0], 0.f); o1[1] = fmaxf(o1[1], 0.f); o1[2] = fmaxf(o1[2], 0.f); o1[3] = fmaxf(o1[3], 0.f);
;         o0 = o0 * o0; o1 = o1 * o1;
;         store_pair16(ACT + (size_t)(brow + rrow) * 4096 + bcol + cb32, pack4(o0), pack4(o1), fq);
;       });
	v_pk_mul_f32 v[30:31], v[30:31], v[32:33] op_sel_hi:[1,0]
	v_pk_mul_f32 v[28:29], v[28:29], v[32:33] op_sel_hi:[1,0]
	v_pk_mul_f32 v[26:27], v[26:27], v[32:33] op_sel_hi:[1,0]
	v_pk_mul_f32 v[24:25], v[24:25], v[32:33] op_sel_hi:[1,0]
	v_add_u32_e32 v34, 0xa0, v128
	v_mov_b32_e32 v35, v129
	v_max_f32_e32 v28, 0, v28
	v_max_f32_e32 v29, 0, v29
	v_max_f32_e32 v30, 0, v30
	v_max_f32_e32 v31, 0, v31
	v_max_f32_e32 v24, 0, v24
	v_max_f32_e32 v25, 0, v25
	v_max_f32_e32 v26, 0, v26
	v_max_f32_e32 v27, 0, v27
	v_lshlrev_b64 v[34:35], 13, v[34:35]
	v_pk_mul_f32 v[30:31], v[30:31], v[30:31]
	v_pk_mul_f32 v[28:29], v[28:29], v[28:29]
	v_pk_mul_f32 v[36:37], v[26:27], v[26:27]
	v_pk_mul_f32 v[26:27], v[24:25], v[24:25]
	v_lshl_add_u64 v[34:35], v[130:131], 0, v[34:35]
	v_cvt_pk_bf16_f32 v24, v28, v29
	v_cvt_pk_bf16_f32 v25, v30, v31
	v_cvt_pk_bf16_f32 v26, v26, v27
	v_cvt_pk_bf16_f32 v27, v36, v37
	v_pk_mul_f32 v[22:23], v[22:23], v[32:33] op_sel_hi:[1,0]
	v_pk_mul_f32 v[20:21], v[20:21], v[32:33] op_sel_hi:[1,0]
	v_pk_mul_f32 v[18:19], v[18:19], v[32:33] op_sel_hi:[1,0]
	v_pk_mul_f32 v[16:17], v[16:17], v[32:33] op_sel_hi:[1,0]
	v_permlane16_swap_b32_e32 v24, v26
	v_permlane16_swap_b32_e32 v25, v27
	v_lshl_add_u64 v[28:29], v[34:35], 0, s[12:13]
	v_max_f32_e32 v20, 0, v20
	v_max_f32_e32 v21, 0, v21
	v_max_f32_e32 v22, 0, v22
	v_max_f32_e32 v23, 0, v23
	v_max_f32_e32 v16, 0, v16
	v_max_f32_e32 v17, 0, v17
	v_max_f32_e32 v18, 0, v18
	v_max_f32_e32 v19, 0, v19
	s_andn2_b64 exec, exec, s[36:37]
	global_store_dwordx4 v[28:29], v[24:27], off
	s_mov_b64 exec, s[36:37]
	global_store_dwordx4 v[28:29], v[24:27], off sc1
	s_mov_b64 exec, -1
	v_pk_mul_f32 v[22:23], v[22:23], v[22:23]
	v_pk_mul_f32 v[20:21], v[20:21], v[20:21]
	v_pk_mul_f32 v[24:25], v[18:19], v[18:19]
	v_pk_mul_f32 v[18:19], v[16:17], v[16:17]
	v_cvt_pk_bf16_f32 v16, v20, v21
	v_cvt_pk_bf16_f32 v17, v22, v23
	v_cvt_pk_bf16_f32 v18, v18, v19
	v_cvt_pk_bf16_f32 v19, v24, v25
	s_nop 0
	v_permlane16_swap_b32_e32 v16, v18
	v_permlane16_swap_b32_e32 v17, v19
	s_andn2_b64 exec, exec, s[36:37]
	global_store_dwordx4 v[28:29], v[16:19], off offset:256
	s_mov_b64 exec, s[36:37]
	global_store_dwordx4 v[28:29], v[16:19], off offset:256 sc1
	s_mov_b64 exec, -1
	v_add_u32_e32 v128, 0xb0, v128
	s_nop 0
	v_mov_b32_e32 v18, v33
	v_pk_mul_f32 v[14:15], v[14:15], v[18:19] op_sel_hi:[1,0]
	v_pk_mul_f32 v[12:13], v[12:13], v[18:19] op_sel_hi:[1,0]
	v_pk_mul_f32 v[10:11], v[10:11], v[18:19] op_sel_hi:[1,0]
	v_pk_mul_f32 v[8:9], v[8:9], v[18:19] op_sel_hi:[1,0]
	v_max_f32_e32 v12, 0, v12
	v_max_f32_e32 v13, 0, v13
	v_max_f32_e32 v14, 0, v14
	v_max_f32_e32 v15, 0, v15
	v_max_f32_e32 v8, 0, v8
	v_max_f32_e32 v9, 0, v9
	v_max_f32_e32 v10, 0, v10
	v_max_f32_e32 v11, 0, v11
	v_lshlrev_b64 v[16:17], 13, v[128:129]
	v_pk_mul_f32 v[14:15], v[14:15], v[14:15]
	v_pk_mul_f32 v[12:13], v[12:13], v[12:13]
	v_pk_mul_f32 v[20:21], v[10:11], v[10:11]
	v_pk_mul_f32 v[10:11], v[8:9], v[8:9]
	v_lshl_add_u64 v[16:17], v[130:131], 0, v[16:17]
	v_cvt_pk_bf16_f32 v8, v12, v13
	v_cvt_pk_bf16_f32 v9, v14, v15
	v_cvt_pk_bf16_f32 v10, v10, v11
	v_cvt_pk_bf16_f32 v11, v20, v21
	v_pk_mul_f32 v[6:7], v[6:7], v[18:19] op_sel_hi:[1,0]
	v_pk_mul_f32 v[4:5], v[4:5], v[18:19] op_sel_hi:[1,0]
	v_pk_mul_f32 v[2:3], v[2:3], v[18:19] op_sel_hi:[1,0]
	v_pk_mul_f32 v[0:1], v[0:1], v[18:19] op_sel_hi:[1,0]
	v_permlane16_swap_b32_e32 v8, v10
	v_permlane16_swap_b32_e32 v9, v11
	v_lshl_add_u64 v[12:13], v[16:17], 0, s[12:13]
	v_max_f32_e32 v4, 0, v4
	v_max_f32_e32 v5, 0, v5
	v_max_f32_e32 v6, 0, v6
	v_max_f32_e32 v7, 0, v7
	v_max_f32_e32 v0, 0, v0
	v_max_f32_e32 v1, 0, v1
	v_max_f32_e32 v2, 0, v2
	v_max_f32_e32 v3, 0, v3
	s_andn2_b64 exec, exec, s[36:37]
	global_store_dwordx4 v[12:13], v[8:11], off
	s_mov_b64 exec, s[36:37]
	global_store_dwordx4 v[12:13], v[8:11], off sc1
	s_mov_b64 exec, -1
	v_pk_mul_f32 v[6:7], v[6:7], v[6:7]
	v_pk_mul_f32 v[4:5], v[4:5], v[4:5]
	v_pk_mul_f32 v[8:9], v[2:3], v[2:3]
	v_pk_mul_f32 v[2:3], v[0:1], v[0:1]
	v_cvt_pk_bf16_f32 v0, v4, v5
	v_cvt_pk_bf16_f32 v1, v6, v7
	v_cvt_pk_bf16_f32 v2, v2, v3
	v_cvt_pk_bf16_f32 v3, v8, v9
	s_nop 0
	v_permlane16_swap_b32_e32 v0, v2
	v_permlane16_swap_b32_e32 v1, v3
	s_andn2_b64 exec, exec, s[36:37]
	global_store_dwordx4 v[12:13], v[0:3], off offset:256
	s_mov_b64 exec, s[36:37]
	global_store_dwordx4 v[12:13], v[0:3], off offset:256 sc1
	s_mov_b64 exec, -1
	s_cbranch_vccz .LBB0_1075
